# GEMM k-loops: first k-tile peeled with C=0 (no accumulator zero-init) on top of hand-written loops + trimmed attention loop
# speedup vs baseline: 1.0374x; 1.0057x over previous
.LBB0_152:
	s_or_saveexec_b64 s[0:1], s[0:1]
	v_mov_b32_e32 v176, 0
	v_mov_b32_e32 v94, 0
	v_mov_b32_e32 v182, 0
	v_mov_b32_e32 v92, 0
	v_mov_b32_e32 v184, 0
	v_mov_b32_e32 v90, 0
	v_mov_b32_e32 v186, 0
	v_mov_b32_e32 v88, 0
	v_mov_b32_e32 v188, 0
	v_mov_b32_e32 v86, 0
	v_mov_b32_e32 v190, 0
	v_mov_b32_e32 v84, 0
	v_mov_b32_e32 v192, 0
	v_mov_b32_e32 v82, 0
	v_mov_b32_e32 v194, 0
	v_mov_b32_e32 v80, 0
	v_mov_b32_e32 v128, 0
	v_mov_b32_e32 v46, 0
	v_mov_b32_e32 v130, 0
	v_mov_b32_e32 v44, 0
	v_mov_b32_e32 v132, 0
	v_mov_b32_e32 v42, 0
	v_mov_b32_e32 v134, 0
	v_mov_b32_e32 v40, 0
	v_mov_b32_e32 v136, 0
	v_mov_b32_e32 v38, 0
	v_mov_b32_e32 v138, 0
	v_mov_b32_e32 v36, 0
	v_mov_b32_e32 v172, 0
	v_mov_b32_e32 v34, 0
	v_mov_b32_e32 v174, 0
	v_mov_b32_e32 v32, 0
	v_mov_b32_e32 v177, 0
	v_mov_b32_e32 v95, 0
	v_mov_b32_e32 v183, 0
	v_mov_b32_e32 v93, 0
	v_mov_b32_e32 v185, 0
	v_mov_b32_e32 v91, 0
	v_mov_b32_e32 v187, 0
	v_mov_b32_e32 v89, 0
	v_mov_b32_e32 v189, 0
	v_mov_b32_e32 v87, 0
	v_mov_b32_e32 v191, 0
	v_mov_b32_e32 v85, 0
	v_mov_b32_e32 v193, 0
	v_mov_b32_e32 v83, 0
	v_mov_b32_e32 v195, 0
	v_mov_b32_e32 v81, 0
	v_mov_b32_e32 v129, 0
	v_mov_b32_e32 v47, 0
	v_mov_b32_e32 v131, 0
	v_mov_b32_e32 v45, 0
	v_mov_b32_e32 v133, 0
	v_mov_b32_e32 v43, 0
	v_mov_b32_e32 v135, 0
	v_mov_b32_e32 v41, 0
	v_mov_b32_e32 v137, 0
	v_mov_b32_e32 v39, 0
	v_mov_b32_e32 v139, 0
	v_mov_b32_e32 v37, 0
	v_mov_b32_e32 v173, 0
	v_mov_b32_e32 v35, 0
	v_mov_b32_e32 v175, 0
	v_mov_b32_e32 v33, 0
	s_xor_b64 exec, exec, s[0:1]
	s_cbranch_execz .LBB0_156
	v_readfirstlane_b32 s78, v170
	v_readfirstlane_b32 s79, v168
	v_readfirstlane_b32 s76, v204
	v_mbcnt_lo_u32_b32 v136, -1, 0
	v_mbcnt_hi_u32_b32 v136, -1, v136
	s_nop 3
	s_lshl_b32 s78, s78, 14
	s_lshl_b32 s79, s79, 13
	s_add_u32 s72, s90, s78
	s_addc_u32 s73, s91, 0
	s_add_u32 s74, s90, s79
	s_addc_u32 s75, s91, 0
	s_add_u32 s74, s74, 0x1ab88000
	s_addc_u32 s75, s75, 0
	v_and_b32_e32 v137, 31, v136
	v_lshrrev_b32_e32 v138, 5, v136
	v_bfe_u32 v139, v136, 2, 2
	v_xor_b32_e32 v138, v138, v139
	v_lshlrev_b32_e32 v138, 4, v138
	v_lshl_or_b32 v137, v137, 6, v138
	v_lshrrev_b32_e32 v139, 10, v204
	v_lshrrev_b32_e32 v138, 1, v139
	v_lshl_or_b32 v128, v138, 11, v137
	v_and_b32_e32 v138, 1, v139
	v_lshl_or_b32 v130, v138, 12, v137
	v_or_b32_e32 v130, 0x4000, v130
	v_xor_b32_e32 v129, 32, v128
	v_xor_b32_e32 v131, 32, v130
	v_lshrrev_b32_e32 v137, 2, v136
	v_lshrrev_b32_e32 v138, 4, v136
	v_xor_b32_e32 v138, v138, v136
	v_and_b32_e32 v138, 3, v138
	v_lshlrev_b32_e32 v138, 4, v138
	v_lshl_or_b32 v137, v137, 6, v138
	v_or_b32_e32 v132, v137, v204
	v_add_u32_e32 v133, 0x1000, v132
	v_add_u32_e32 v134, 0x2000, v132
	v_add_u32_e32 v135, 0x3000, v132
	s_add_u32 m0, s76, 0x2000
	s_nop 0
	global_load_lds_dwordx4 v134, s[72:73]
	s_add_u32 m0, s76, 0x3000
	s_nop 0
	global_load_lds_dwordx4 v135, s[72:73]
	s_add_u32 m0, s76, 0x4000
	s_nop 0
	global_load_lds_dwordx4 v132, s[74:75]
	s_add_u32 m0, s76, 0x5000
	s_nop 0
	global_load_lds_dwordx4 v133, s[74:75]
	s_add_u32 s72, s72, 0x202000
	s_addc_u32 s73, s73, 0
	s_add_u32 s74, s74, 0x2c000
	s_addc_u32 s75, s75, 0
	s_add_u32 m0, s76, 0x6000
	s_nop 0
	global_load_lds_dwordx4 v132, s[72:73]
	s_add_u32 m0, s76, 0x7000
	s_nop 0
	global_load_lds_dwordx4 v133, s[72:73]
	s_add_u32 m0, s76, 0x8000
	s_nop 0
	global_load_lds_dwordx4 v134, s[72:73]
	s_add_u32 m0, s76, 0x9000
	s_nop 0
	global_load_lds_dwordx4 v135, s[72:73]
	s_add_u32 m0, s76, 0xa000
	s_nop 0
	global_load_lds_dwordx4 v132, s[74:75]
	s_add_u32 m0, s76, 0xb000
	s_nop 0
	global_load_lds_dwordx4 v133, s[74:75]
	s_add_u32 s72, s72, 0x202000
	s_addc_u32 s73, s73, 0
	s_add_u32 s74, s74, 0x2c000
	s_addc_u32 s75, s75, 0
	s_add_u32 m0, s76, 0xc000
	s_nop 0
	global_load_lds_dwordx4 v132, s[72:73]
	s_add_u32 m0, s76, 0xd000
	s_nop 0
	global_load_lds_dwordx4 v133, s[72:73]
	s_add_u32 m0, s76, 0xe000
	s_nop 0
	global_load_lds_dwordx4 v134, s[72:73]
	s_add_u32 m0, s76, 0xf000
	s_nop 0
	global_load_lds_dwordx4 v135, s[72:73]
	s_add_u32 m0, s76, 0x10000
	s_nop 0
	global_load_lds_dwordx4 v132, s[74:75]
	s_add_u32 m0, s76, 0x11000
	s_nop 0
	global_load_lds_dwordx4 v133, s[74:75]
	s_add_u32 s72, s72, 0x202000
	s_addc_u32 s73, s73, 0
	s_add_u32 s74, s74, 0x2c000
	s_addc_u32 s75, s75, 0
	s_waitcnt vmcnt(12)
	s_barrier
	ds_read_b128 v[172:175], v130
	ds_read_b128 v[176:179], v130 offset:2048
	ds_read_b128 v[180:183], v128
	ds_read_b128 v[184:187], v128 offset:4096
	ds_read_b128 v[188:191], v128 offset:8192
	ds_read_b128 v[192:195], v128 offset:12288
	s_waitcnt lgkmcnt(0)
	ds_read_b128 v[220:223], v131
	ds_read_b128 v[224:227], v131 offset:2048
	v_mfma_f32_32x32x16_bf16 v[64:79], v[172:175], v[180:183], 0
	ds_read_b128 v[228:231], v129
	ds_read_b128 v[232:235], v129 offset:4096
	v_mfma_f32_32x32x16_bf16 v[48:63], v[176:179], v[180:183], 0
	ds_read_b128 v[236:239], v129 offset:8192
	ds_read_b128 v[240:243], v129 offset:12288
	v_mfma_f32_32x32x16_bf16 v[16:31], v[172:175], v[184:187], 0
	v_mfma_f32_32x32x16_bf16 v[0:15], v[176:179], v[184:187], 0
	v_mfma_f32_32x32x16_bf16 v[80:95], v[172:175], v[188:191], 0
	v_mfma_f32_32x32x16_bf16 v[112:127], v[176:179], v[188:191], 0
	v_mfma_f32_32x32x16_bf16 v[32:47], v[172:175], v[192:195], 0
	v_mfma_f32_32x32x16_bf16 v[96:111], v[176:179], v[192:195], 0
	s_waitcnt lgkmcnt(0)
	s_waitcnt vmcnt(6)
	s_barrier
	ds_read_b128 v[172:175], v130 offset:24576
	ds_read_b128 v[176:179], v130 offset:26624
	v_mfma_f32_32x32x16_bf16 v[64:79], v[220:223], v[228:231], v[64:79]
	ds_read_b128 v[180:183], v128 offset:24576
	ds_read_b128 v[184:187], v128 offset:28672
	v_mfma_f32_32x32x16_bf16 v[48:63], v[224:227], v[228:231], v[48:63]
	ds_read_b128 v[188:191], v128 offset:32768
	ds_read_b128 v[192:195], v128 offset:36864
	v_mfma_f32_32x32x16_bf16 v[16:31], v[220:223], v[232:235], v[16:31]
	s_add_u32 m0, s76, 0x0
	v_mfma_f32_32x32x16_bf16 v[0:15], v[224:227], v[232:235], v[0:15]
	global_load_lds_dwordx4 v132, s[72:73]
	s_add_u32 m0, s76, 0x1000
	v_mfma_f32_32x32x16_bf16 v[80:95], v[220:223], v[236:239], v[80:95]
	global_load_lds_dwordx4 v133, s[72:73]
	s_add_u32 m0, s76, 0x2000
	v_mfma_f32_32x32x16_bf16 v[112:127], v[224:227], v[236:239], v[112:127]
	global_load_lds_dwordx4 v134, s[72:73]
	s_add_u32 m0, s76, 0x3000
	v_mfma_f32_32x32x16_bf16 v[32:47], v[220:223], v[240:243], v[32:47]
	global_load_lds_dwordx4 v135, s[72:73]
	s_add_u32 m0, s76, 0x4000
	v_mfma_f32_32x32x16_bf16 v[96:111], v[224:227], v[240:243], v[96:111]
	global_load_lds_dwordx4 v132, s[74:75]
	s_add_u32 m0, s76, 0x5000
	s_add_u32 s72, s72, 0x202000
	s_addc_u32 s73, s73, 0
	global_load_lds_dwordx4 v133, s[74:75]
	s_add_u32 s74, s74, 0x2c000
	s_addc_u32 s75, s75, 0
	s_waitcnt lgkmcnt(0)
	ds_read_b128 v[220:223], v131 offset:24576
	ds_read_b128 v[224:227], v131 offset:26624
	v_mfma_f32_32x32x16_bf16 v[64:79], v[172:175], v[180:183], v[64:79]
	ds_read_b128 v[228:231], v129 offset:24576
	ds_read_b128 v[232:235], v129 offset:28672
	v_mfma_f32_32x32x16_bf16 v[48:63], v[176:179], v[180:183], v[48:63]
	ds_read_b128 v[236:239], v129 offset:32768
	ds_read_b128 v[240:243], v129 offset:36864
	v_mfma_f32_32x32x16_bf16 v[16:31], v[172:175], v[184:187], v[16:31]
	v_mfma_f32_32x32x16_bf16 v[0:15], v[176:179], v[184:187], v[0:15]
	v_mfma_f32_32x32x16_bf16 v[80:95], v[172:175], v[188:191], v[80:95]
	v_mfma_f32_32x32x16_bf16 v[112:127], v[176:179], v[188:191], v[112:127]
	v_mfma_f32_32x32x16_bf16 v[32:47], v[172:175], v[192:195], v[32:47]
	v_mfma_f32_32x32x16_bf16 v[96:111], v[176:179], v[192:195], v[96:111]
	s_waitcnt lgkmcnt(0)
	s_waitcnt vmcnt(6)
	s_barrier
	ds_read_b128 v[172:175], v130 offset:49152
	ds_read_b128 v[176:179], v130 offset:51200
	v_mfma_f32_32x32x16_bf16 v[64:79], v[220:223], v[228:231], v[64:79]
	ds_read_b128 v[180:183], v128 offset:49152
	ds_read_b128 v[184:187], v128 offset:53248
	v_mfma_f32_32x32x16_bf16 v[48:63], v[224:227], v[228:231], v[48:63]
	ds_read_b128 v[188:191], v128 offset:57344
	ds_read_b128 v[192:195], v128 offset:61440
	v_mfma_f32_32x32x16_bf16 v[16:31], v[220:223], v[232:235], v[16:31]
	s_add_u32 m0, s76, 0x6000
	v_mfma_f32_32x32x16_bf16 v[0:15], v[224:227], v[232:235], v[0:15]
	global_load_lds_dwordx4 v132, s[72:73]
	s_add_u32 m0, s76, 0x7000
	v_mfma_f32_32x32x16_bf16 v[80:95], v[220:223], v[236:239], v[80:95]
	global_load_lds_dwordx4 v133, s[72:73]
	s_add_u32 m0, s76, 0x8000
	v_mfma_f32_32x32x16_bf16 v[112:127], v[224:227], v[236:239], v[112:127]
	global_load_lds_dwordx4 v134, s[72:73]
	s_add_u32 m0, s76, 0x9000
	v_mfma_f32_32x32x16_bf16 v[32:47], v[220:223], v[240:243], v[32:47]
	global_load_lds_dwordx4 v135, s[72:73]
	s_add_u32 m0, s76, 0xa000
	v_mfma_f32_32x32x16_bf16 v[96:111], v[224:227], v[240:243], v[96:111]
	global_load_lds_dwordx4 v132, s[74:75]
	s_add_u32 m0, s76, 0xb000
	s_add_u32 s72, s72, 0x202000
	s_addc_u32 s73, s73, 0
	global_load_lds_dwordx4 v133, s[74:75]
	s_add_u32 s74, s74, 0x2c000
	s_addc_u32 s75, s75, 0
	s_waitcnt lgkmcnt(0)
	ds_read_b128 v[220:223], v131 offset:49152
	ds_read_b128 v[224:227], v131 offset:51200
	v_mfma_f32_32x32x16_bf16 v[64:79], v[172:175], v[180:183], v[64:79]
	ds_read_b128 v[228:231], v129 offset:49152
	ds_read_b128 v[232:235], v129 offset:53248
	v_mfma_f32_32x32x16_bf16 v[48:63], v[176:179], v[180:183], v[48:63]
	ds_read_b128 v[236:239], v129 offset:57344
	ds_read_b128 v[240:243], v129 offset:61440
	v_mfma_f32_32x32x16_bf16 v[16:31], v[172:175], v[184:187], v[16:31]
	v_mfma_f32_32x32x16_bf16 v[0:15], v[176:179], v[184:187], v[0:15]
	v_mfma_f32_32x32x16_bf16 v[80:95], v[172:175], v[188:191], v[80:95]
	v_mfma_f32_32x32x16_bf16 v[112:127], v[176:179], v[188:191], v[112:127]
	v_mfma_f32_32x32x16_bf16 v[32:47], v[172:175], v[192:195], v[32:47]
	v_mfma_f32_32x32x16_bf16 v[96:111], v[176:179], v[192:195], v[96:111]
	s_waitcnt lgkmcnt(0)
	s_waitcnt vmcnt(6)
	s_barrier
	ds_read_b128 v[172:175], v130
	ds_read_b128 v[176:179], v130 offset:2048
	v_mfma_f32_32x32x16_bf16 v[64:79], v[220:223], v[228:231], v[64:79]
	ds_read_b128 v[180:183], v128
	ds_read_b128 v[184:187], v128 offset:4096
	v_mfma_f32_32x32x16_bf16 v[48:63], v[224:227], v[228:231], v[48:63]
	ds_read_b128 v[188:191], v128 offset:8192
	ds_read_b128 v[192:195], v128 offset:12288
	v_mfma_f32_32x32x16_bf16 v[16:31], v[220:223], v[232:235], v[16:31]
	s_add_u32 m0, s76, 0xc000
	v_mfma_f32_32x32x16_bf16 v[0:15], v[224:227], v[232:235], v[0:15]
	global_load_lds_dwordx4 v132, s[72:73]
	s_add_u32 m0, s76, 0xd000
	v_mfma_f32_32x32x16_bf16 v[80:95], v[220:223], v[236:239], v[80:95]
	global_load_lds_dwordx4 v133, s[72:73]
	s_add_u32 m0, s76, 0xe000
	v_mfma_f32_32x32x16_bf16 v[112:127], v[224:227], v[236:239], v[112:127]
	global_load_lds_dwordx4 v134, s[72:73]
	s_add_u32 m0, s76, 0xf000
	v_mfma_f32_32x32x16_bf16 v[32:47], v[220:223], v[240:243], v[32:47]
	global_load_lds_dwordx4 v135, s[72:73]
	s_add_u32 m0, s76, 0x10000
	v_mfma_f32_32x32x16_bf16 v[96:111], v[224:227], v[240:243], v[96:111]
	global_load_lds_dwordx4 v132, s[74:75]
	s_add_u32 m0, s76, 0x11000
	s_add_u32 s72, s72, 0x202000
	s_addc_u32 s73, s73, 0
	global_load_lds_dwordx4 v133, s[74:75]
	s_add_u32 s74, s74, 0x2c000
	s_addc_u32 s75, s75, 0
	s_waitcnt lgkmcnt(0)
	s_mov_b32 s77, 8

.LBB0_535:
	s_or_saveexec_b64 s[0:1], s[0:1]
	v_mov_b32_e32 v127, 0
	v_mov_b64_e32 v[130:131], s[18:19]
	v_mov_b32_e32 v126, 0
	v_mov_b32_e32 v125, 0
	v_mov_b32_e32 v124, 0
	v_mov_b32_e32 v123, 0
	v_mov_b32_e32 v122, 0
	v_mov_b32_e32 v121, 0
	v_mov_b32_e32 v120, 0
	v_mov_b32_e32 v119, 0
	v_mov_b32_e32 v118, 0
	v_mov_b32_e32 v117, 0
	v_mov_b32_e32 v116, 0
	v_mov_b32_e32 v115, 0
	v_mov_b32_e32 v114, 0
	v_mov_b32_e32 v113, 0
	v_mov_b32_e32 v112, 0
	v_mov_b32_e32 v63, 0
	v_mov_b32_e32 v62, 0
	v_mov_b32_e32 v61, 0
	v_mov_b32_e32 v60, 0
	v_mov_b32_e32 v59, 0
	v_mov_b32_e32 v58, 0
	v_mov_b32_e32 v57, 0
	v_mov_b32_e32 v56, 0
	v_mov_b32_e32 v55, 0
	v_mov_b32_e32 v54, 0
	v_mov_b32_e32 v53, 0
	v_mov_b32_e32 v52, 0
	v_mov_b32_e32 v51, 0
	v_mov_b32_e32 v50, 0
	v_mov_b32_e32 v49, 0
	v_mov_b32_e32 v48, 0
	v_mov_b32_e32 v111, 0
	v_mov_b32_e32 v110, 0
	v_mov_b32_e32 v109, 0
	v_mov_b32_e32 v108, 0
	v_mov_b32_e32 v107, 0
	v_mov_b32_e32 v106, 0
	v_mov_b32_e32 v105, 0
	v_mov_b32_e32 v104, 0
	v_mov_b32_e32 v103, 0
	v_mov_b32_e32 v102, 0
	v_mov_b32_e32 v101, 0
	v_mov_b32_e32 v100, 0
	v_mov_b32_e32 v99, 0
	v_mov_b32_e32 v98, 0
	v_mov_b32_e32 v97, 0
	v_mov_b32_e32 v96, 0
	v_mov_b32_e32 v47, 0
	v_mov_b32_e32 v46, 0
	v_mov_b32_e32 v45, 0
	v_mov_b32_e32 v44, 0
	v_mov_b32_e32 v43, 0
	v_mov_b32_e32 v42, 0
	v_mov_b32_e32 v41, 0
	v_mov_b32_e32 v40, 0
	v_mov_b32_e32 v39, 0
	v_mov_b32_e32 v38, 0
	v_mov_b32_e32 v37, 0
	v_mov_b32_e32 v36, 0
	v_mov_b32_e32 v35, 0
	v_mov_b32_e32 v34, 0
	v_mov_b32_e32 v33, 0
	v_mov_b32_e32 v32, 0
	s_xor_b64 exec, exec, s[0:1]
	s_cbranch_execz .LBB0_539
	v_readfirstlane_b32 s78, v166
	v_readfirstlane_b32 s79, v168
	v_readfirstlane_b32 s76, v186
	v_mbcnt_lo_u32_b32 v244, -1, 0
	v_mbcnt_hi_u32_b32 v244, -1, v244
	s_nop 3
	s_lshl_b32 s78, s78, 14
	s_lshl_b32 s79, s79, 13
	s_add_u32 s72, s90, s78
	s_addc_u32 s73, s91, 0
	s_add_u32 s72, s72, 0xf0f0000
	s_addc_u32 s73, s73, 0
	s_add_u32 s74, s90, s79
	s_addc_u32 s75, s91, 0
	s_add_u32 s74, s74, 0x1b108000
	s_addc_u32 s75, s75, 0
	v_and_b32_e32 v245, 31, v244
	v_lshrrev_b32_e32 v246, 5, v244
	v_bfe_u32 v247, v244, 2, 2
	v_xor_b32_e32 v246, v246, v247
	v_lshlrev_b32_e32 v246, 4, v246
	v_lshl_or_b32 v245, v245, 6, v246
	v_lshrrev_b32_e32 v247, 10, v186
	v_lshrrev_b32_e32 v246, 1, v247
	v_lshl_or_b32 v128, v246, 11, v245
	v_and_b32_e32 v246, 1, v247
	v_lshl_or_b32 v167, v246, 12, v245
	v_or_b32_e32 v167, 0x4000, v167
	v_xor_b32_e32 v129, 32, v128
	v_xor_b32_e32 v169, 32, v167
	v_lshrrev_b32_e32 v245, 2, v244
	v_lshrrev_b32_e32 v246, 4, v244
	v_xor_b32_e32 v246, v246, v244
	v_and_b32_e32 v246, 3, v246
	v_lshlrev_b32_e32 v246, 4, v246
	v_lshl_or_b32 v245, v245, 6, v246
	v_or_b32_e32 v170, v245, v186
	v_add_u32_e32 v171, 0x1000, v170
	v_add_u32_e32 v180, 0x2000, v170
	v_add_u32_e32 v181, 0x3000, v170
	s_add_u32 m0, s76, 0x2000
	s_nop 0
	global_load_lds_dwordx4 v180, s[72:73]
	s_add_u32 m0, s76, 0x3000
	s_nop 0
	global_load_lds_dwordx4 v181, s[72:73]
	s_add_u32 m0, s76, 0x4000
	s_nop 0
	global_load_lds_dwordx4 v170, s[74:75]
	s_add_u32 m0, s76, 0x5000
	s_nop 0
	global_load_lds_dwordx4 v171, s[74:75]
	s_add_u32 s72, s72, 0x202000
	s_addc_u32 s73, s73, 0
	s_add_u32 s74, s74, 0x10000
	s_addc_u32 s75, s75, 0
	s_add_u32 m0, s76, 0x6000
	s_nop 0
	global_load_lds_dwordx4 v170, s[72:73]
	s_add_u32 m0, s76, 0x7000
	s_nop 0
	global_load_lds_dwordx4 v171, s[72:73]
	s_add_u32 m0, s76, 0x8000
	s_nop 0
	global_load_lds_dwordx4 v180, s[72:73]
	s_add_u32 m0, s76, 0x9000
	s_nop 0
	global_load_lds_dwordx4 v181, s[72:73]
	s_add_u32 m0, s76, 0xa000
	s_nop 0
	global_load_lds_dwordx4 v170, s[74:75]
	s_add_u32 m0, s76, 0xb000
	s_nop 0
	global_load_lds_dwordx4 v171, s[74:75]
	s_add_u32 s72, s72, 0x202000
	s_addc_u32 s73, s73, 0
	s_add_u32 s74, s74, 0x10000
	s_addc_u32 s75, s75, 0
	s_add_u32 m0, s76, 0xc000
	s_nop 0
	global_load_lds_dwordx4 v170, s[72:73]
	s_add_u32 m0, s76, 0xd000
	s_nop 0
	global_load_lds_dwordx4 v171, s[72:73]
	s_add_u32 m0, s76, 0xe000
	s_nop 0
	global_load_lds_dwordx4 v180, s[72:73]
	s_add_u32 m0, s76, 0xf000
	s_nop 0
	global_load_lds_dwordx4 v181, s[72:73]
	s_add_u32 m0, s76, 0x10000
	s_nop 0
	global_load_lds_dwordx4 v170, s[74:75]
	s_add_u32 m0, s76, 0x11000
	s_nop 0
	global_load_lds_dwordx4 v171, s[74:75]
	s_add_u32 s72, s72, 0x202000
	s_addc_u32 s73, s73, 0
	s_add_u32 s74, s74, 0x10000
	s_addc_u32 s75, s75, 0
	s_waitcnt vmcnt(12)
	s_barrier
	ds_read_b128 v[212:215], v167
	ds_read_b128 v[216:219], v167 offset:2048
	ds_read_b128 v[220:223], v128
	ds_read_b128 v[224:227], v128 offset:4096
	ds_read_b128 v[228:231], v128 offset:8192
	ds_read_b128 v[232:235], v128 offset:12288
	s_waitcnt lgkmcnt(0)
	ds_read_b128 v[236:239], v169
	ds_read_b128 v[240:243], v169 offset:2048
	v_mfma_f32_32x32x16_bf16 v[80:95], v[212:215], v[220:223], 0
	ds_read_b128 v[132:135], v129
	ds_read_b128 v[136:139], v129 offset:4096
	v_mfma_f32_32x32x16_bf16 v[64:79], v[216:219], v[220:223], 0
	ds_read_b128 v[172:175], v129 offset:8192
	ds_read_b128 v[176:179], v129 offset:12288
	v_mfma_f32_32x32x16_bf16 v[16:31], v[212:215], v[224:227], 0
	v_mfma_f32_32x32x16_bf16 v[0:15], v[216:219], v[224:227], 0
	v_mfma_f32_32x32x16_bf16 v[112:127], v[212:215], v[228:231], 0
	v_mfma_f32_32x32x16_bf16 v[96:111], v[216:219], v[228:231], 0
	v_mfma_f32_32x32x16_bf16 v[48:63], v[212:215], v[232:235], 0
	v_mfma_f32_32x32x16_bf16 v[32:47], v[216:219], v[232:235], 0
	s_waitcnt lgkmcnt(0)
	s_waitcnt vmcnt(6)
	s_barrier
	ds_read_b128 v[212:215], v167 offset:24576
	ds_read_b128 v[216:219], v167 offset:26624
	v_mfma_f32_32x32x16_bf16 v[80:95], v[236:239], v[132:135], v[80:95]
	ds_read_b128 v[220:223], v128 offset:24576
	ds_read_b128 v[224:227], v128 offset:28672
	v_mfma_f32_32x32x16_bf16 v[64:79], v[240:243], v[132:135], v[64:79]
	ds_read_b128 v[228:231], v128 offset:32768
	ds_read_b128 v[232:235], v128 offset:36864
	v_mfma_f32_32x32x16_bf16 v[16:31], v[236:239], v[136:139], v[16:31]
	s_add_u32 m0, s76, 0x0
	v_mfma_f32_32x32x16_bf16 v[0:15], v[240:243], v[136:139], v[0:15]
	global_load_lds_dwordx4 v170, s[72:73]
	s_add_u32 m0, s76, 0x1000
	v_mfma_f32_32x32x16_bf16 v[112:127], v[236:239], v[172:175], v[112:127]
	global_load_lds_dwordx4 v171, s[72:73]
	s_add_u32 m0, s76, 0x2000
	v_mfma_f32_32x32x16_bf16 v[96:111], v[240:243], v[172:175], v[96:111]
	global_load_lds_dwordx4 v180, s[72:73]
	s_add_u32 m0, s76, 0x3000
	v_mfma_f32_32x32x16_bf16 v[48:63], v[236:239], v[176:179], v[48:63]
	global_load_lds_dwordx4 v181, s[72:73]
	s_add_u32 m0, s76, 0x4000
	v_mfma_f32_32x32x16_bf16 v[32:47], v[240:243], v[176:179], v[32:47]
	global_load_lds_dwordx4 v170, s[74:75]
	s_add_u32 m0, s76, 0x5000
	s_add_u32 s72, s72, 0x202000
	s_addc_u32 s73, s73, 0
	global_load_lds_dwordx4 v171, s[74:75]
	s_add_u32 s74, s74, 0x10000
	s_addc_u32 s75, s75, 0
	s_waitcnt lgkmcnt(0)
	ds_read_b128 v[236:239], v169 offset:24576
	ds_read_b128 v[240:243], v169 offset:26624
	v_mfma_f32_32x32x16_bf16 v[80:95], v[212:215], v[220:223], v[80:95]
	ds_read_b128 v[132:135], v129 offset:24576
	ds_read_b128 v[136:139], v129 offset:28672
	v_mfma_f32_32x32x16_bf16 v[64:79], v[216:219], v[220:223], v[64:79]
	ds_read_b128 v[172:175], v129 offset:32768
	ds_read_b128 v[176:179], v129 offset:36864
	v_mfma_f32_32x32x16_bf16 v[16:31], v[212:215], v[224:227], v[16:31]
	v_mfma_f32_32x32x16_bf16 v[0:15], v[216:219], v[224:227], v[0:15]
	v_mfma_f32_32x32x16_bf16 v[112:127], v[212:215], v[228:231], v[112:127]
	v_mfma_f32_32x32x16_bf16 v[96:111], v[216:219], v[228:231], v[96:111]
	v_mfma_f32_32x32x16_bf16 v[48:63], v[212:215], v[232:235], v[48:63]
	v_mfma_f32_32x32x16_bf16 v[32:47], v[216:219], v[232:235], v[32:47]
	s_waitcnt lgkmcnt(0)
	s_waitcnt vmcnt(6)
	s_barrier
	ds_read_b128 v[212:215], v167 offset:49152
	ds_read_b128 v[216:219], v167 offset:51200
	v_mfma_f32_32x32x16_bf16 v[80:95], v[236:239], v[132:135], v[80:95]
	ds_read_b128 v[220:223], v128 offset:49152
	ds_read_b128 v[224:227], v128 offset:53248
	v_mfma_f32_32x32x16_bf16 v[64:79], v[240:243], v[132:135], v[64:79]
	ds_read_b128 v[228:231], v128 offset:57344
	ds_read_b128 v[232:235], v128 offset:61440
	v_mfma_f32_32x32x16_bf16 v[16:31], v[236:239], v[136:139], v[16:31]
	s_add_u32 m0, s76, 0x6000
	v_mfma_f32_32x32x16_bf16 v[0:15], v[240:243], v[136:139], v[0:15]
	global_load_lds_dwordx4 v170, s[72:73]
	s_add_u32 m0, s76, 0x7000
	v_mfma_f32_32x32x16_bf16 v[112:127], v[236:239], v[172:175], v[112:127]
	global_load_lds_dwordx4 v171, s[72:73]
	s_add_u32 m0, s76, 0x8000
	v_mfma_f32_32x32x16_bf16 v[96:111], v[240:243], v[172:175], v[96:111]
	global_load_lds_dwordx4 v180, s[72:73]
	s_add_u32 m0, s76, 0x9000
	v_mfma_f32_32x32x16_bf16 v[48:63], v[236:239], v[176:179], v[48:63]
	global_load_lds_dwordx4 v181, s[72:73]
	s_add_u32 m0, s76, 0xa000
	v_mfma_f32_32x32x16_bf16 v[32:47], v[240:243], v[176:179], v[32:47]
	global_load_lds_dwordx4 v170, s[74:75]
	s_add_u32 m0, s76, 0xb000
	s_add_u32 s72, s72, 0x202000
	s_addc_u32 s73, s73, 0
	global_load_lds_dwordx4 v171, s[74:75]
	s_add_u32 s74, s74, 0x10000
	s_addc_u32 s75, s75, 0
	s_waitcnt lgkmcnt(0)
	ds_read_b128 v[236:239], v169 offset:49152
	ds_read_b128 v[240:243], v169 offset:51200
	v_mfma_f32_32x32x16_bf16 v[80:95], v[212:215], v[220:223], v[80:95]
	ds_read_b128 v[132:135], v129 offset:49152
	ds_read_b128 v[136:139], v129 offset:53248
	v_mfma_f32_32x32x16_bf16 v[64:79], v[216:219], v[220:223], v[64:79]
	ds_read_b128 v[172:175], v129 offset:57344
	ds_read_b128 v[176:179], v129 offset:61440
	v_mfma_f32_32x32x16_bf16 v[16:31], v[212:215], v[224:227], v[16:31]
	v_mfma_f32_32x32x16_bf16 v[0:15], v[216:219], v[224:227], v[0:15]
	v_mfma_f32_32x32x16_bf16 v[112:127], v[212:215], v[228:231], v[112:127]
	v_mfma_f32_32x32x16_bf16 v[96:111], v[216:219], v[228:231], v[96:111]
	v_mfma_f32_32x32x16_bf16 v[48:63], v[212:215], v[232:235], v[48:63]
	v_mfma_f32_32x32x16_bf16 v[32:47], v[216:219], v[232:235], v[32:47]
	s_waitcnt lgkmcnt(0)
	s_waitcnt vmcnt(6)
	s_barrier
	ds_read_b128 v[212:215], v167
	ds_read_b128 v[216:219], v167 offset:2048
	v_mfma_f32_32x32x16_bf16 v[80:95], v[236:239], v[132:135], v[80:95]
	ds_read_b128 v[220:223], v128
	ds_read_b128 v[224:227], v128 offset:4096
	v_mfma_f32_32x32x16_bf16 v[64:79], v[240:243], v[132:135], v[64:79]
	ds_read_b128 v[228:231], v128 offset:8192
	ds_read_b128 v[232:235], v128 offset:12288
	v_mfma_f32_32x32x16_bf16 v[16:31], v[236:239], v[136:139], v[16:31]
	s_add_u32 m0, s76, 0xc000
	v_mfma_f32_32x32x16_bf16 v[0:15], v[240:243], v[136:139], v[0:15]
	global_load_lds_dwordx4 v170, s[72:73]
	s_add_u32 m0, s76, 0xd000
	v_mfma_f32_32x32x16_bf16 v[112:127], v[236:239], v[172:175], v[112:127]
	global_load_lds_dwordx4 v171, s[72:73]
	s_add_u32 m0, s76, 0xe000
	v_mfma_f32_32x32x16_bf16 v[96:111], v[240:243], v[172:175], v[96:111]
	global_load_lds_dwordx4 v180, s[72:73]
	s_add_u32 m0, s76, 0xf000
	v_mfma_f32_32x32x16_bf16 v[48:63], v[236:239], v[176:179], v[48:63]
	global_load_lds_dwordx4 v181, s[72:73]
	s_add_u32 m0, s76, 0x10000
	v_mfma_f32_32x32x16_bf16 v[32:47], v[240:243], v[176:179], v[32:47]
	global_load_lds_dwordx4 v170, s[74:75]
	s_add_u32 m0, s76, 0x11000
	s_add_u32 s72, s72, 0x202000
	s_addc_u32 s73, s73, 0
	global_load_lds_dwordx4 v171, s[74:75]
	s_add_u32 s74, s74, 0x10000
	s_addc_u32 s75, s75, 0
	s_waitcnt lgkmcnt(0)
	s_mov_b32 s77, 12

.LBB0_630:
	s_or_saveexec_b64 s[0:1], s[0:1]
	v_mov_b32_e32 v63, 0
	v_mov_b32_e32 v62, 0
	v_mov_b32_e32 v61, 0
	v_mov_b32_e32 v60, 0
	v_mov_b32_e32 v59, 0
	v_mov_b32_e32 v58, 0
	v_mov_b32_e32 v57, 0
	v_mov_b32_e32 v56, 0
	v_mov_b32_e32 v55, 0
	v_mov_b32_e32 v54, 0
	v_mov_b32_e32 v53, 0
	v_mov_b32_e32 v52, 0
	v_mov_b32_e32 v51, 0
	v_mov_b32_e32 v50, 0
	v_mov_b32_e32 v49, 0
	v_mov_b32_e32 v48, v63
	v_mov_b32_e32 v31, 0
	v_mov_b32_e32 v30, 0
	v_mov_b32_e32 v29, 0
	v_mov_b32_e32 v28, 0
	v_mov_b32_e32 v27, 0
	v_mov_b32_e32 v26, 0
	v_mov_b32_e32 v25, 0
	v_mov_b32_e32 v24, 0
	v_mov_b32_e32 v23, 0
	v_mov_b32_e32 v22, 0
	v_mov_b32_e32 v21, 0
	v_mov_b32_e32 v20, 0
	v_mov_b32_e32 v19, 0
	v_mov_b32_e32 v18, 0
	v_mov_b32_e32 v17, 0
	v_mov_b32_e32 v16, v63
	v_mov_b32_e32 v47, 0
	v_mov_b32_e32 v46, v63
	v_mov_b32_e32 v45, 0
	v_mov_b32_e32 v44, v63
	v_mov_b32_e32 v43, 0
	v_mov_b32_e32 v42, v63
	v_mov_b32_e32 v41, 0
	v_mov_b32_e32 v40, v63
	v_mov_b32_e32 v39, 0
	v_mov_b32_e32 v38, v63
	v_mov_b32_e32 v37, 0
	v_mov_b32_e32 v36, 0
	v_mov_b32_e32 v35, 0
	v_mov_b32_e32 v34, 0
	v_mov_b32_e32 v33, 0
	v_mov_b32_e32 v32, v63
	v_mov_b32_e32 v15, 0
	v_mov_b32_e32 v14, v63
	v_mov_b32_e32 v13, 0
	v_mov_b32_e32 v12, v63
	v_mov_b32_e32 v11, 0
	v_mov_b32_e32 v10, v63
	v_mov_b32_e32 v9, 0
	v_mov_b32_e32 v8, v63
	v_mov_b32_e32 v7, 0
	v_mov_b32_e32 v6, v63
	v_mov_b32_e32 v5, 0
	v_mov_b32_e32 v4, 0
	v_mov_b32_e32 v3, 0
	v_mov_b32_e32 v2, 0
	v_mov_b32_e32 v1, 0
	v_mov_b32_e32 v0, v63
	s_xor_b64 exec, exec, s[0:1]
	s_cbranch_execz .LBB0_634
	v_readfirstlane_b32 s10, v128
	v_readfirstlane_b32 s11, v130
	v_readfirstlane_b32 s8, v226
	v_mbcnt_lo_u32_b32 v192, -1, 0
	v_mbcnt_hi_u32_b32 v192, -1, v192
	s_nop 3
	s_lshl_b32 s10, s10, 14
	s_lshl_b32 s11, s11, 13
	s_add_u32 s4, s90, s10
	s_addc_u32 s5, s91, 0
	s_add_u32 s6, s90, s11
	s_addc_u32 s7, s91, 0
	s_add_u32 s6, s6, 0x1b3c8000
	s_addc_u32 s7, s7, 0
	v_and_b32_e32 v193, 31, v192
	v_lshrrev_b32_e32 v194, 5, v192
	v_bfe_u32 v195, v192, 2, 2
	v_xor_b32_e32 v194, v194, v195
	v_lshlrev_b32_e32 v194, 4, v194
	v_lshl_or_b32 v193, v193, 6, v194
	v_lshrrev_b32_e32 v195, 10, v226
	v_lshrrev_b32_e32 v194, 1, v195
	v_lshl_or_b32 v129, v194, 11, v193
	v_and_b32_e32 v194, 1, v195
	v_lshl_or_b32 v156, v194, 12, v193
	v_or_b32_e32 v156, 0x4000, v156
	v_xor_b32_e32 v131, 32, v129
	v_xor_b32_e32 v188, 32, v156
	v_lshrrev_b32_e32 v193, 2, v192
	v_lshrrev_b32_e32 v194, 4, v192
	v_xor_b32_e32 v194, v194, v192
	v_and_b32_e32 v194, 3, v194
	v_lshlrev_b32_e32 v194, 4, v194
	v_lshl_or_b32 v193, v193, 6, v194
	v_or_b32_e32 v189, v193, v226
	v_add_u32_e32 v252, 0x1000, v189
	v_add_u32_e32 v190, 0x2000, v189
	v_add_u32_e32 v191, 0x3000, v189
	s_add_u32 m0, s8, 0x2000
	s_nop 0
	global_load_lds_dwordx4 v190, s[4:5]
	s_add_u32 m0, s8, 0x3000
	s_nop 0
	global_load_lds_dwordx4 v191, s[4:5]
	s_add_u32 m0, s8, 0x4000
	s_nop 0
	global_load_lds_dwordx4 v189, s[6:7]
	s_add_u32 m0, s8, 0x5000
	s_nop 0
	global_load_lds_dwordx4 v252, s[6:7]
	s_add_u32 s4, s4, 0x202000
	s_addc_u32 s5, s5, 0
	s_add_u32 s6, s6, 0x40000
	s_addc_u32 s7, s7, 0
	s_add_u32 m0, s8, 0x6000
	s_nop 0
	global_load_lds_dwordx4 v189, s[4:5]
	s_add_u32 m0, s8, 0x7000
	s_nop 0
	global_load_lds_dwordx4 v252, s[4:5]
	s_add_u32 m0, s8, 0x8000
	s_nop 0
	global_load_lds_dwordx4 v190, s[4:5]
	s_add_u32 m0, s8, 0x9000
	s_nop 0
	global_load_lds_dwordx4 v191, s[4:5]
	s_add_u32 m0, s8, 0xa000
	s_nop 0
	global_load_lds_dwordx4 v189, s[6:7]
	s_add_u32 m0, s8, 0xb000
	s_nop 0
	global_load_lds_dwordx4 v252, s[6:7]
	s_add_u32 s4, s4, 0x202000
	s_addc_u32 s5, s5, 0
	s_add_u32 s6, s6, 0x40000
	s_addc_u32 s7, s7, 0
	s_add_u32 m0, s8, 0xc000
	s_nop 0
	global_load_lds_dwordx4 v189, s[4:5]
	s_add_u32 m0, s8, 0xd000
	s_nop 0
	global_load_lds_dwordx4 v252, s[4:5]
	s_add_u32 m0, s8, 0xe000
	s_nop 0
	global_load_lds_dwordx4 v190, s[4:5]
	s_add_u32 m0, s8, 0xf000
	s_nop 0
	global_load_lds_dwordx4 v191, s[4:5]
	s_add_u32 m0, s8, 0x10000
	s_nop 0
	global_load_lds_dwordx4 v189, s[6:7]
	s_add_u32 m0, s8, 0x11000
	s_nop 0
	global_load_lds_dwordx4 v252, s[6:7]
	s_add_u32 s4, s4, 0x202000
	s_addc_u32 s5, s5, 0
	s_add_u32 s6, s6, 0x40000
	s_addc_u32 s7, s7, 0
	s_waitcnt vmcnt(12)
	s_barrier
	ds_read_b128 v[132:135], v156
	ds_read_b128 v[136:139], v156 offset:2048
	ds_read_b128 v[140:143], v129
	ds_read_b128 v[180:183], v129 offset:4096
	ds_read_b128 v[184:187], v129 offset:8192
	ds_read_b128 v[236:239], v129 offset:12288
	s_waitcnt lgkmcnt(0)
	ds_read_b128 v[240:243], v188
	ds_read_b128 v[244:247], v188 offset:2048
	v_mfma_f32_32x32x16_bf16 v[112:127], v[132:135], v[140:143], 0
	ds_read_b128 v[248:251], v131
	ds_read_b128 v[200:203], v131 offset:4096
	v_mfma_f32_32x32x16_bf16 v[96:111], v[136:139], v[140:143], 0
	ds_read_b128 v[204:207], v131 offset:8192
	ds_read_b128 v[208:211], v131 offset:12288
	v_mfma_f32_32x32x16_bf16 v[80:95], v[132:135], v[180:183], 0
	v_mfma_f32_32x32x16_bf16 v[64:79], v[136:139], v[180:183], 0
	v_mfma_f32_32x32x16_bf16 v[48:63], v[132:135], v[184:187], 0
	v_mfma_f32_32x32x16_bf16 v[32:47], v[136:139], v[184:187], 0
	v_mfma_f32_32x32x16_bf16 v[16:31], v[132:135], v[236:239], 0
	v_mfma_f32_32x32x16_bf16 v[0:15], v[136:139], v[236:239], 0
	s_waitcnt lgkmcnt(0)
	s_waitcnt vmcnt(6)
	s_barrier
	ds_read_b128 v[132:135], v156 offset:24576
	ds_read_b128 v[136:139], v156 offset:26624
	v_mfma_f32_32x32x16_bf16 v[112:127], v[240:243], v[248:251], v[112:127]
	ds_read_b128 v[140:143], v129 offset:24576
	ds_read_b128 v[180:183], v129 offset:28672
	v_mfma_f32_32x32x16_bf16 v[96:111], v[244:247], v[248:251], v[96:111]
	ds_read_b128 v[184:187], v129 offset:32768
	ds_read_b128 v[236:239], v129 offset:36864
	v_mfma_f32_32x32x16_bf16 v[80:95], v[240:243], v[200:203], v[80:95]
	s_add_u32 m0, s8, 0x0
	v_mfma_f32_32x32x16_bf16 v[64:79], v[244:247], v[200:203], v[64:79]
	global_load_lds_dwordx4 v189, s[4:5]
	s_add_u32 m0, s8, 0x1000
	v_mfma_f32_32x32x16_bf16 v[48:63], v[240:243], v[204:207], v[48:63]
	global_load_lds_dwordx4 v252, s[4:5]
	s_add_u32 m0, s8, 0x2000
	v_mfma_f32_32x32x16_bf16 v[32:47], v[244:247], v[204:207], v[32:47]
	global_load_lds_dwordx4 v190, s[4:5]
	s_add_u32 m0, s8, 0x3000
	v_mfma_f32_32x32x16_bf16 v[16:31], v[240:243], v[208:211], v[16:31]
	global_load_lds_dwordx4 v191, s[4:5]
	s_add_u32 m0, s8, 0x4000
	v_mfma_f32_32x32x16_bf16 v[0:15], v[244:247], v[208:211], v[0:15]
	global_load_lds_dwordx4 v189, s[6:7]
	s_add_u32 m0, s8, 0x5000
	s_add_u32 s4, s4, 0x202000
	s_addc_u32 s5, s5, 0
	global_load_lds_dwordx4 v252, s[6:7]
	s_add_u32 s6, s6, 0x40000
	s_addc_u32 s7, s7, 0
	s_waitcnt lgkmcnt(0)
	ds_read_b128 v[240:243], v188 offset:24576
	ds_read_b128 v[244:247], v188 offset:26624
	v_mfma_f32_32x32x16_bf16 v[112:127], v[132:135], v[140:143], v[112:127]
	ds_read_b128 v[248:251], v131 offset:24576
	ds_read_b128 v[200:203], v131 offset:28672
	v_mfma_f32_32x32x16_bf16 v[96:111], v[136:139], v[140:143], v[96:111]
	ds_read_b128 v[204:207], v131 offset:32768
	ds_read_b128 v[208:211], v131 offset:36864
	v_mfma_f32_32x32x16_bf16 v[80:95], v[132:135], v[180:183], v[80:95]
	v_mfma_f32_32x32x16_bf16 v[64:79], v[136:139], v[180:183], v[64:79]
	v_mfma_f32_32x32x16_bf16 v[48:63], v[132:135], v[184:187], v[48:63]
	v_mfma_f32_32x32x16_bf16 v[32:47], v[136:139], v[184:187], v[32:47]
	v_mfma_f32_32x32x16_bf16 v[16:31], v[132:135], v[236:239], v[16:31]
	v_mfma_f32_32x32x16_bf16 v[0:15], v[136:139], v[236:239], v[0:15]
	s_waitcnt lgkmcnt(0)
	s_waitcnt vmcnt(6)
	s_barrier
	ds_read_b128 v[132:135], v156 offset:49152
	ds_read_b128 v[136:139], v156 offset:51200
	v_mfma_f32_32x32x16_bf16 v[112:127], v[240:243], v[248:251], v[112:127]
	ds_read_b128 v[140:143], v129 offset:49152
	ds_read_b128 v[180:183], v129 offset:53248
	v_mfma_f32_32x32x16_bf16 v[96:111], v[244:247], v[248:251], v[96:111]
	ds_read_b128 v[184:187], v129 offset:57344
	ds_read_b128 v[236:239], v129 offset:61440
	v_mfma_f32_32x32x16_bf16 v[80:95], v[240:243], v[200:203], v[80:95]
	s_add_u32 m0, s8, 0x6000
	v_mfma_f32_32x32x16_bf16 v[64:79], v[244:247], v[200:203], v[64:79]
	global_load_lds_dwordx4 v189, s[4:5]
	s_add_u32 m0, s8, 0x7000
	v_mfma_f32_32x32x16_bf16 v[48:63], v[240:243], v[204:207], v[48:63]
	global_load_lds_dwordx4 v252, s[4:5]
	s_add_u32 m0, s8, 0x8000
	v_mfma_f32_32x32x16_bf16 v[32:47], v[244:247], v[204:207], v[32:47]
	global_load_lds_dwordx4 v190, s[4:5]
	s_add_u32 m0, s8, 0x9000
	v_mfma_f32_32x32x16_bf16 v[16:31], v[240:243], v[208:211], v[16:31]
	global_load_lds_dwordx4 v191, s[4:5]
	s_add_u32 m0, s8, 0xa000
	v_mfma_f32_32x32x16_bf16 v[0:15], v[244:247], v[208:211], v[0:15]
	global_load_lds_dwordx4 v189, s[6:7]
	s_add_u32 m0, s8, 0xb000
	s_add_u32 s4, s4, 0x202000
	s_addc_u32 s5, s5, 0
	global_load_lds_dwordx4 v252, s[6:7]
	s_add_u32 s6, s6, 0x40000
	s_addc_u32 s7, s7, 0
	s_waitcnt lgkmcnt(0)
	ds_read_b128 v[240:243], v188 offset:49152
	ds_read_b128 v[244:247], v188 offset:51200
	v_mfma_f32_32x32x16_bf16 v[112:127], v[132:135], v[140:143], v[112:127]
	ds_read_b128 v[248:251], v131 offset:49152
	ds_read_b128 v[200:203], v131 offset:53248
	v_mfma_f32_32x32x16_bf16 v[96:111], v[136:139], v[140:143], v[96:111]
	ds_read_b128 v[204:207], v131 offset:57344
	ds_read_b128 v[208:211], v131 offset:61440
	v_mfma_f32_32x32x16_bf16 v[80:95], v[132:135], v[180:183], v[80:95]
	v_mfma_f32_32x32x16_bf16 v[64:79], v[136:139], v[180:183], v[64:79]
	v_mfma_f32_32x32x16_bf16 v[48:63], v[132:135], v[184:187], v[48:63]
	v_mfma_f32_32x32x16_bf16 v[32:47], v[136:139], v[184:187], v[32:47]
	v_mfma_f32_32x32x16_bf16 v[16:31], v[132:135], v[236:239], v[16:31]
	v_mfma_f32_32x32x16_bf16 v[0:15], v[136:139], v[236:239], v[0:15]
	s_waitcnt lgkmcnt(0)
	s_waitcnt vmcnt(6)
	s_barrier
	ds_read_b128 v[132:135], v156
	ds_read_b128 v[136:139], v156 offset:2048
	v_mfma_f32_32x32x16_bf16 v[112:127], v[240:243], v[248:251], v[112:127]
	ds_read_b128 v[140:143], v129
	ds_read_b128 v[180:183], v129 offset:4096
	v_mfma_f32_32x32x16_bf16 v[96:111], v[244:247], v[248:251], v[96:111]
	ds_read_b128 v[184:187], v129 offset:8192
	ds_read_b128 v[236:239], v129 offset:12288
	v_mfma_f32_32x32x16_bf16 v[80:95], v[240:243], v[200:203], v[80:95]
	s_add_u32 m0, s8, 0xc000
	v_mfma_f32_32x32x16_bf16 v[64:79], v[244:247], v[200:203], v[64:79]
	global_load_lds_dwordx4 v189, s[4:5]
	s_add_u32 m0, s8, 0xd000
	v_mfma_f32_32x32x16_bf16 v[48:63], v[240:243], v[204:207], v[48:63]
	global_load_lds_dwordx4 v252, s[4:5]
	s_add_u32 m0, s8, 0xe000
	v_mfma_f32_32x32x16_bf16 v[32:47], v[244:247], v[204:207], v[32:47]
	global_load_lds_dwordx4 v190, s[4:5]
	s_add_u32 m0, s8, 0xf000
	v_mfma_f32_32x32x16_bf16 v[16:31], v[240:243], v[208:211], v[16:31]
	global_load_lds_dwordx4 v191, s[4:5]
	s_add_u32 m0, s8, 0x10000
	v_mfma_f32_32x32x16_bf16 v[0:15], v[244:247], v[208:211], v[0:15]
	global_load_lds_dwordx4 v189, s[6:7]
	s_add_u32 m0, s8, 0x11000
	s_add_u32 s4, s4, 0x202000
	s_addc_u32 s5, s5, 0
	global_load_lds_dwordx4 v252, s[6:7]
	s_add_u32 s6, s6, 0x40000
	s_addc_u32 s7, s7, 0
	s_waitcnt lgkmcnt(0)
	s_mov_b32 s9, 8

.LBB0_887:
	s_or_saveexec_b64 s[0:1], s[0:1]
	v_mov_b32_e32 v127, 0
	v_mov_b32_e32 v126, 0
	v_mov_b32_e32 v125, 0
	v_mov_b32_e32 v124, 0
	v_mov_b32_e32 v123, 0
	v_mov_b32_e32 v122, 0
	v_mov_b32_e32 v121, 0
	v_mov_b32_e32 v120, 0
	v_mov_b32_e32 v119, 0
	v_mov_b32_e32 v118, 0
	v_mov_b32_e32 v117, 0
	v_mov_b32_e32 v116, 0
	v_mov_b32_e32 v115, 0
	v_mov_b32_e32 v114, 0
	v_mov_b32_e32 v113, 0
	v_mov_b32_e32 v112, 0
	v_mov_b32_e32 v63, 0
	v_mov_b32_e32 v62, 0
	v_mov_b32_e32 v61, 0
	v_mov_b32_e32 v60, 0
	v_mov_b32_e32 v59, 0
	v_mov_b32_e32 v58, 0
	v_mov_b32_e32 v57, 0
	v_mov_b32_e32 v56, 0
	v_mov_b32_e32 v55, 0
	v_mov_b32_e32 v54, 0
	v_mov_b32_e32 v53, 0
	v_mov_b32_e32 v52, 0
	v_mov_b32_e32 v51, 0
	v_mov_b32_e32 v50, 0
	v_mov_b32_e32 v49, 0
	v_mov_b32_e32 v48, 0
	v_mov_b32_e32 v111, 0
	v_mov_b32_e32 v110, 0
	v_mov_b32_e32 v109, 0
	v_mov_b32_e32 v108, 0
	v_mov_b32_e32 v107, 0
	v_mov_b32_e32 v106, 0
	v_mov_b32_e32 v105, 0
	v_mov_b32_e32 v104, 0
	v_mov_b32_e32 v103, 0
	v_mov_b32_e32 v102, 0
	v_mov_b32_e32 v101, 0
	v_mov_b32_e32 v100, 0
	v_mov_b32_e32 v99, 0
	v_mov_b32_e32 v98, 0
	v_mov_b32_e32 v97, 0
	v_mov_b32_e32 v96, 0
	v_mov_b32_e32 v47, 0
	v_mov_b32_e32 v46, 0
	v_mov_b32_e32 v45, 0
	v_mov_b32_e32 v44, 0
	v_mov_b32_e32 v43, 0
	v_mov_b32_e32 v42, 0
	v_mov_b32_e32 v41, 0
	v_mov_b32_e32 v40, 0
	v_mov_b32_e32 v39, 0
	v_mov_b32_e32 v38, 0
	v_mov_b32_e32 v37, 0
	v_mov_b32_e32 v36, 0
	v_mov_b32_e32 v35, 0
	v_mov_b32_e32 v34, 0
	v_mov_b32_e32 v33, 0
	v_mov_b32_e32 v32, 0
	s_xor_b64 exec, exec, s[0:1]
	s_cbranch_execz .LBB0_891
	v_readfirstlane_b32 s78, v148
	v_readfirstlane_b32 s79, v150
	v_readfirstlane_b32 s76, v178
	v_mbcnt_lo_u32_b32 v164, -1, 0
	v_mbcnt_hi_u32_b32 v164, -1, v164
	s_nop 3
	s_lshl_b32 s78, s78, 14
	s_lshl_b32 s79, s79, 13
	s_add_u32 s72, s90, s78
	s_addc_u32 s73, s91, 0
	s_add_u32 s74, s90, s79
	s_addc_u32 s75, s91, 0
	s_add_u32 s74, s74, 0x1bbc8000
	s_addc_u32 s75, s75, 0
	v_and_b32_e32 v165, 31, v164
	v_lshrrev_b32_e32 v166, 5, v164
	v_bfe_u32 v167, v164, 2, 2
	v_xor_b32_e32 v166, v166, v167
	v_lshlrev_b32_e32 v166, 4, v166
	v_lshl_or_b32 v165, v165, 6, v166
	v_lshrrev_b32_e32 v167, 10, v178
	v_lshrrev_b32_e32 v166, 1, v167
	v_lshl_or_b32 v156, v166, 11, v165
	v_and_b32_e32 v166, 1, v167
	v_lshl_or_b32 v158, v166, 12, v165
	v_or_b32_e32 v158, 0x4000, v158
	v_xor_b32_e32 v157, 32, v156
	v_xor_b32_e32 v159, 32, v158
	v_lshrrev_b32_e32 v165, 2, v164
	v_lshrrev_b32_e32 v166, 4, v164
	v_xor_b32_e32 v166, v166, v164
	v_and_b32_e32 v166, 3, v166
	v_lshlrev_b32_e32 v166, 4, v166
	v_lshl_or_b32 v165, v165, 6, v166
	v_or_b32_e32 v160, v165, v178
	v_add_u32_e32 v161, 0x1000, v160
	v_add_u32_e32 v162, 0x2000, v160
	v_add_u32_e32 v163, 0x3000, v160
	s_add_u32 m0, s76, 0x2000
	s_nop 0
	global_load_lds_dwordx4 v162, s[72:73]
	s_add_u32 m0, s76, 0x3000
	s_nop 0
	global_load_lds_dwordx4 v163, s[72:73]
	s_add_u32 m0, s76, 0x4000
	s_nop 0
	global_load_lds_dwordx4 v160, s[74:75]
	s_add_u32 m0, s76, 0x5000
	s_nop 0
	global_load_lds_dwordx4 v161, s[74:75]
	s_add_u32 s72, s72, 0x202000
	s_addc_u32 s73, s73, 0
	s_add_u32 s74, s74, 0x10000
	s_addc_u32 s75, s75, 0
	s_add_u32 m0, s76, 0x6000
	s_nop 0
	global_load_lds_dwordx4 v160, s[72:73]
	s_add_u32 m0, s76, 0x7000
	s_nop 0
	global_load_lds_dwordx4 v161, s[72:73]
	s_add_u32 m0, s76, 0x8000
	s_nop 0
	global_load_lds_dwordx4 v162, s[72:73]
	s_add_u32 m0, s76, 0x9000
	s_nop 0
	global_load_lds_dwordx4 v163, s[72:73]
	s_add_u32 m0, s76, 0xa000
	s_nop 0
	global_load_lds_dwordx4 v160, s[74:75]
	s_add_u32 m0, s76, 0xb000
	s_nop 0
	global_load_lds_dwordx4 v161, s[74:75]
	s_add_u32 s72, s72, 0x202000
	s_addc_u32 s73, s73, 0
	s_add_u32 s74, s74, 0x10000
	s_addc_u32 s75, s75, 0
	s_add_u32 m0, s76, 0xc000
	s_nop 0
	global_load_lds_dwordx4 v160, s[72:73]
	s_add_u32 m0, s76, 0xd000
	s_nop 0
	global_load_lds_dwordx4 v161, s[72:73]
	s_add_u32 m0, s76, 0xe000
	s_nop 0
	global_load_lds_dwordx4 v162, s[72:73]
	s_add_u32 m0, s76, 0xf000
	s_nop 0
	global_load_lds_dwordx4 v163, s[72:73]
	s_add_u32 m0, s76, 0x10000
	s_nop 0
	global_load_lds_dwordx4 v160, s[74:75]
	s_add_u32 m0, s76, 0x11000
	s_nop 0
	global_load_lds_dwordx4 v161, s[74:75]
	s_add_u32 s72, s72, 0x202000
	s_addc_u32 s73, s73, 0
	s_add_u32 s74, s74, 0x10000
	s_addc_u32 s75, s75, 0
	s_waitcnt vmcnt(12)
	s_barrier
	ds_read_b128 v[200:203], v158
	ds_read_b128 v[204:207], v158 offset:2048
	ds_read_b128 v[208:211], v156
	ds_read_b128 v[212:215], v156 offset:4096
	ds_read_b128 v[216:219], v156 offset:8192
	ds_read_b128 v[220:223], v156 offset:12288
	s_waitcnt lgkmcnt(0)
	ds_read_b128 v[224:227], v159
	ds_read_b128 v[228:231], v159 offset:2048
	v_mfma_f32_32x32x16_bf16 v[80:95], v[200:203], v[208:211], 0
	ds_read_b128 v[232:235], v157
	ds_read_b128 v[236:239], v157 offset:4096
	v_mfma_f32_32x32x16_bf16 v[64:79], v[204:207], v[208:211], 0
	ds_read_b128 v[240:243], v157 offset:8192
	ds_read_b128 v[152:155], v157 offset:12288
	v_mfma_f32_32x32x16_bf16 v[16:31], v[200:203], v[212:215], 0
	v_mfma_f32_32x32x16_bf16 v[0:15], v[204:207], v[212:215], 0
	v_mfma_f32_32x32x16_bf16 v[112:127], v[200:203], v[216:219], 0
	v_mfma_f32_32x32x16_bf16 v[96:111], v[204:207], v[216:219], 0
	v_mfma_f32_32x32x16_bf16 v[48:63], v[200:203], v[220:223], 0
	v_mfma_f32_32x32x16_bf16 v[32:47], v[204:207], v[220:223], 0
	s_waitcnt lgkmcnt(0)
	s_waitcnt vmcnt(6)
	s_barrier
	ds_read_b128 v[200:203], v158 offset:24576
	ds_read_b128 v[204:207], v158 offset:26624
	v_mfma_f32_32x32x16_bf16 v[80:95], v[224:227], v[232:235], v[80:95]
	ds_read_b128 v[208:211], v156 offset:24576
	ds_read_b128 v[212:215], v156 offset:28672
	v_mfma_f32_32x32x16_bf16 v[64:79], v[228:231], v[232:235], v[64:79]
	ds_read_b128 v[216:219], v156 offset:32768
	ds_read_b128 v[220:223], v156 offset:36864
	v_mfma_f32_32x32x16_bf16 v[16:31], v[224:227], v[236:239], v[16:31]
	s_add_u32 m0, s76, 0x0
	v_mfma_f32_32x32x16_bf16 v[0:15], v[228:231], v[236:239], v[0:15]
	global_load_lds_dwordx4 v160, s[72:73]
	s_add_u32 m0, s76, 0x1000
	v_mfma_f32_32x32x16_bf16 v[112:127], v[224:227], v[240:243], v[112:127]
	global_load_lds_dwordx4 v161, s[72:73]
	s_add_u32 m0, s76, 0x2000
	v_mfma_f32_32x32x16_bf16 v[96:111], v[228:231], v[240:243], v[96:111]
	global_load_lds_dwordx4 v162, s[72:73]
	s_add_u32 m0, s76, 0x3000
	v_mfma_f32_32x32x16_bf16 v[48:63], v[224:227], v[152:155], v[48:63]
	global_load_lds_dwordx4 v163, s[72:73]
	s_add_u32 m0, s76, 0x4000
	v_mfma_f32_32x32x16_bf16 v[32:47], v[228:231], v[152:155], v[32:47]
	global_load_lds_dwordx4 v160, s[74:75]
	s_add_u32 m0, s76, 0x5000
	s_add_u32 s72, s72, 0x202000
	s_addc_u32 s73, s73, 0
	global_load_lds_dwordx4 v161, s[74:75]
	s_add_u32 s74, s74, 0x10000
	s_addc_u32 s75, s75, 0
	s_waitcnt lgkmcnt(0)
	ds_read_b128 v[224:227], v159 offset:24576
	ds_read_b128 v[228:231], v159 offset:26624
	v_mfma_f32_32x32x16_bf16 v[80:95], v[200:203], v[208:211], v[80:95]
	ds_read_b128 v[232:235], v157 offset:24576
	ds_read_b128 v[236:239], v157 offset:28672
	v_mfma_f32_32x32x16_bf16 v[64:79], v[204:207], v[208:211], v[64:79]
	ds_read_b128 v[240:243], v157 offset:32768
	ds_read_b128 v[152:155], v157 offset:36864
	v_mfma_f32_32x32x16_bf16 v[16:31], v[200:203], v[212:215], v[16:31]
	v_mfma_f32_32x32x16_bf16 v[0:15], v[204:207], v[212:215], v[0:15]
	v_mfma_f32_32x32x16_bf16 v[112:127], v[200:203], v[216:219], v[112:127]
	v_mfma_f32_32x32x16_bf16 v[96:111], v[204:207], v[216:219], v[96:111]
	v_mfma_f32_32x32x16_bf16 v[48:63], v[200:203], v[220:223], v[48:63]
	v_mfma_f32_32x32x16_bf16 v[32:47], v[204:207], v[220:223], v[32:47]
	s_waitcnt lgkmcnt(0)
	s_waitcnt vmcnt(6)
	s_barrier
	ds_read_b128 v[200:203], v158 offset:49152
	ds_read_b128 v[204:207], v158 offset:51200
	v_mfma_f32_32x32x16_bf16 v[80:95], v[224:227], v[232:235], v[80:95]
	ds_read_b128 v[208:211], v156 offset:49152
	ds_read_b128 v[212:215], v156 offset:53248
	v_mfma_f32_32x32x16_bf16 v[64:79], v[228:231], v[232:235], v[64:79]
	ds_read_b128 v[216:219], v156 offset:57344
	ds_read_b128 v[220:223], v156 offset:61440
	v_mfma_f32_32x32x16_bf16 v[16:31], v[224:227], v[236:239], v[16:31]
	s_add_u32 m0, s76, 0x6000
	v_mfma_f32_32x32x16_bf16 v[0:15], v[228:231], v[236:239], v[0:15]
	global_load_lds_dwordx4 v160, s[72:73]
	s_add_u32 m0, s76, 0x7000
	v_mfma_f32_32x32x16_bf16 v[112:127], v[224:227], v[240:243], v[112:127]
	global_load_lds_dwordx4 v161, s[72:73]
	s_add_u32 m0, s76, 0x8000
	v_mfma_f32_32x32x16_bf16 v[96:111], v[228:231], v[240:243], v[96:111]
	global_load_lds_dwordx4 v162, s[72:73]
	s_add_u32 m0, s76, 0x9000
	v_mfma_f32_32x32x16_bf16 v[48:63], v[224:227], v[152:155], v[48:63]
	global_load_lds_dwordx4 v163, s[72:73]
	s_add_u32 m0, s76, 0xa000
	v_mfma_f32_32x32x16_bf16 v[32:47], v[228:231], v[152:155], v[32:47]
	global_load_lds_dwordx4 v160, s[74:75]
	s_add_u32 m0, s76, 0xb000
	s_add_u32 s72, s72, 0x202000
	s_addc_u32 s73, s73, 0
	global_load_lds_dwordx4 v161, s[74:75]
	s_add_u32 s74, s74, 0x10000
	s_addc_u32 s75, s75, 0
	s_waitcnt lgkmcnt(0)
	ds_read_b128 v[224:227], v159 offset:49152
	ds_read_b128 v[228:231], v159 offset:51200
	v_mfma_f32_32x32x16_bf16 v[80:95], v[200:203], v[208:211], v[80:95]
	ds_read_b128 v[232:235], v157 offset:49152
	ds_read_b128 v[236:239], v157 offset:53248
	v_mfma_f32_32x32x16_bf16 v[64:79], v[204:207], v[208:211], v[64:79]
	ds_read_b128 v[240:243], v157 offset:57344
	ds_read_b128 v[152:155], v157 offset:61440
	v_mfma_f32_32x32x16_bf16 v[16:31], v[200:203], v[212:215], v[16:31]
	v_mfma_f32_32x32x16_bf16 v[0:15], v[204:207], v[212:215], v[0:15]
	v_mfma_f32_32x32x16_bf16 v[112:127], v[200:203], v[216:219], v[112:127]
	v_mfma_f32_32x32x16_bf16 v[96:111], v[204:207], v[216:219], v[96:111]
	v_mfma_f32_32x32x16_bf16 v[48:63], v[200:203], v[220:223], v[48:63]
	v_mfma_f32_32x32x16_bf16 v[32:47], v[204:207], v[220:223], v[32:47]
	s_waitcnt lgkmcnt(0)
	s_waitcnt vmcnt(6)
	s_barrier
	ds_read_b128 v[200:203], v158
	ds_read_b128 v[204:207], v158 offset:2048
	v_mfma_f32_32x32x16_bf16 v[80:95], v[224:227], v[232:235], v[80:95]
	ds_read_b128 v[208:211], v156
	ds_read_b128 v[212:215], v156 offset:4096
	v_mfma_f32_32x32x16_bf16 v[64:79], v[228:231], v[232:235], v[64:79]
	ds_read_b128 v[216:219], v156 offset:8192
	ds_read_b128 v[220:223], v156 offset:12288
	v_mfma_f32_32x32x16_bf16 v[16:31], v[224:227], v[236:239], v[16:31]
	s_add_u32 m0, s76, 0xc000
	v_mfma_f32_32x32x16_bf16 v[0:15], v[228:231], v[236:239], v[0:15]
	global_load_lds_dwordx4 v160, s[72:73]
	s_add_u32 m0, s76, 0xd000
	v_mfma_f32_32x32x16_bf16 v[112:127], v[224:227], v[240:243], v[112:127]
	global_load_lds_dwordx4 v161, s[72:73]
	s_add_u32 m0, s76, 0xe000
	v_mfma_f32_32x32x16_bf16 v[96:111], v[228:231], v[240:243], v[96:111]
	global_load_lds_dwordx4 v162, s[72:73]
	s_add_u32 m0, s76, 0xf000
	v_mfma_f32_32x32x16_bf16 v[48:63], v[224:227], v[152:155], v[48:63]
	global_load_lds_dwordx4 v163, s[72:73]
	s_add_u32 m0, s76, 0x10000
	v_mfma_f32_32x32x16_bf16 v[32:47], v[228:231], v[152:155], v[32:47]
	global_load_lds_dwordx4 v160, s[74:75]
	s_add_u32 m0, s76, 0x11000
	s_add_u32 s72, s72, 0x202000
	s_addc_u32 s73, s73, 0
	global_load_lds_dwordx4 v161, s[74:75]
	s_add_u32 s74, s74, 0x10000
	s_addc_u32 s75, s75, 0
	s_waitcnt lgkmcnt(0)
	s_mov_b32 s77, 8
